# RWKV output stage: 8 tokens' group-norm statistics reduced together (transposed quad reduce + row_ror + permlane swaps), loads hoisted, one pass of elementwise per token
# speedup vs baseline: 1.0056x; 1.0056x over previous
.LBB0_2490:
	s_mov_b64 s[72:73], -1
	s_and_b64 vcc, exec, s[20:21]
	s_cbranch_vccz .LBB0_2514
	s_cmp_eq_u32 s42, 0
	s_cselect_b64 s[72:73], -1, 0
	s_and_b64 vcc, exec, s[72:73]
	s_cbranch_vccnz .LBB0_2493
	s_add_i32 s0, s42, -1
	s_lshl_b32 s50, s0, 13
	s_and_b32 s50, s50, 0x2000
	s_add_i32 s72, s50, 0
	s_add_i32 s52, s72, 0x1a000
	s_add_i32 s72, s72, 0x1e000
	s_and_b32 s1, s0, 0xff
	s_mulk_i32 s1, 0xab
	s_lshr_b32 s1, s1, 9
	s_mul_i32 s1, s1, 3
	s_sub_i32 s1, s0, s1
	s_and_b32 s1, s1, 0xff
	s_lshl_b32 s43, s1, 13
	s_add_i32 s43, s43, 0x14000
	s_lshl_b32 s0, s0, 5
	s_add_u32 vcc_lo, s84, s0
	s_addc_u32 vcc_hi, s85, 0
	s_lshl_b32 s0, s1, 7
	s_add_i32 s0, s41, s0
	v_mov_b32_e32 v0, s0
	v_mov_b32_e32 v16, v225
	v_mov_b32_e32 v17, v224
	v_mov_b32_e32 v18, v223
	v_mov_b32_e32 v19, v221
	v_mov_b32_e32 v20, v242
	v_mov_b32_e32 v22, v227
	v_mov_b32_e32 v23, v226
	v_mov_b32_e32 v24, v222
	v_mov_b32_e32 v25, v218
	v_mov_b32_e32 v26, v217
	v_mov_b32_e32 v27, v216
	v_mov_b32_e32 v29, v215
	s_mov_b32 s98, 0xaaaaaaaa
	s_mov_b32 s99, 0xaaaaaaaa
	s_mov_b32 s100, 0xcccccccc
	s_mov_b32 s101, 0xcccccccc
	v_add_u32_e32 v1, s72, v124
	ds_read_b32 v66, v1
	v_add_u32_e32 v1, s72, v128
	ds_read_b32 v67, v1
	v_add_u32_e32 v1, s72, v132
	ds_read_b32 v68, v1
	v_add_u32_e32 v1, s72, v136
	ds_read_b32 v69, v1
	v_add_u32_e32 v1, s72, v140
	ds_read_b32 v70, v1
	v_add_u32_e32 v1, s72, v144
	ds_read_b32 v71, v1
	v_add_u32_e32 v1, s72, v148
	ds_read_b32 v72, v1
	v_add_u32_e32 v1, s72, v152
	ds_read_b32 v73, v1
	s_waitcnt lgkmcnt(0)
	v_add_u32_e32 v1, s43, v124
	ds_read_b32 v90, v1
	v_add_u32_e32 v2, s52, v124
	ds_read_b32 v98, v2
	ds_read_b32 v106, v0
	v_add_u32_e32 v1, s43, v128
	ds_read_b32 v91, v1
	v_add_u32_e32 v2, s52, v128
	ds_read_b32 v99, v2
	ds_read_b32 v107, v0 offset:4
	v_add_u32_e32 v1, s43, v132
	ds_read_b32 v92, v1
	v_add_u32_e32 v2, s52, v132
	ds_read_b32 v100, v2
	ds_read_b32 v108, v0 offset:8
	v_add_u32_e32 v1, s43, v136
	ds_read_b32 v93, v1
	v_add_u32_e32 v2, s52, v136
	ds_read_b32 v101, v2
	ds_read_b32 v109, v0 offset:12
	v_add_u32_e32 v1, s43, v140
	ds_read_b32 v94, v1
	v_add_u32_e32 v2, s52, v140
	ds_read_b32 v102, v2
	ds_read_b32 v110, v0 offset:16
	v_add_u32_e32 v1, s43, v144
	ds_read_b32 v95, v1
	v_add_u32_e32 v2, s52, v144
	ds_read_b32 v103, v2
	ds_read_b32 v111, v0 offset:20
	v_add_u32_e32 v1, s43, v148
	ds_read_b32 v96, v1
	v_add_u32_e32 v2, s52, v148
	ds_read_b32 v104, v2
	ds_read_b32 v112, v0 offset:24
	v_add_u32_e32 v1, s43, v152
	ds_read_b32 v97, v1
	v_add_u32_e32 v2, s52, v152
	ds_read_b32 v105, v2
	ds_read_b32 v113, v0 offset:28
	v_cndmask_b32_e64 v115, v67, v66, s[98:99]
	v_cndmask_b32_e64 v117, v69, v68, s[98:99]
	v_cndmask_b32_e64 v119, v71, v70, s[98:99]
	v_cndmask_b32_e64 v121, v73, v72, s[98:99]
	v_cndmask_b32_e64 v114, v66, v67, s[98:99]
	v_cndmask_b32_e64 v116, v68, v69, s[98:99]
	v_cndmask_b32_e64 v118, v70, v71, s[98:99]
	v_cndmask_b32_e64 v120, v72, v73, s[98:99]
	v_add_f32_dpp v114, v115, v114 quad_perm:[1,0,3,2] row_mask:0xf bank_mask:0xf bound_ctrl:1
	v_add_f32_dpp v116, v117, v116 quad_perm:[1,0,3,2] row_mask:0xf bank_mask:0xf bound_ctrl:1
	v_add_f32_dpp v118, v119, v118 quad_perm:[1,0,3,2] row_mask:0xf bank_mask:0xf bound_ctrl:1
	v_add_f32_dpp v120, v121, v120 quad_perm:[1,0,3,2] row_mask:0xf bank_mask:0xf bound_ctrl:1
	v_cndmask_b32_e64 v115, v116, v114, s[100:101]
	v_cndmask_b32_e64 v119, v120, v118, s[100:101]
	v_cndmask_b32_e64 v114, v114, v116, s[100:101]
	v_cndmask_b32_e64 v118, v118, v120, s[100:101]
	v_add_f32_dpp v114, v115, v114 quad_perm:[2,3,0,1] row_mask:0xf bank_mask:0xf bound_ctrl:1
	v_add_f32_dpp v118, v119, v118 quad_perm:[2,3,0,1] row_mask:0xf bank_mask:0xf bound_ctrl:1
	s_nop 0
	v_add_f32_dpp v114, v114, v114 row_ror:4 row_mask:0xf bank_mask:0xf
	v_add_f32_dpp v118, v118, v118 row_ror:4 row_mask:0xf bank_mask:0xf
	s_nop 0
	v_add_f32_dpp v114, v114, v114 row_ror:8 row_mask:0xf bank_mask:0xf
	v_add_f32_dpp v118, v118, v118 row_ror:8 row_mask:0xf bank_mask:0xf
	v_mov_b32_e32 v115, v114
	v_mov_b32_e32 v119, v118
	s_nop 1
	v_permlane16_swap_b32_e32 v115, v114
	v_permlane16_swap_b32_e32 v119, v118
	v_add_f32_e32 v114, v114, v115
	v_add_f32_e32 v118, v118, v119
	v_mov_b32_e32 v115, v114
	v_mov_b32_e32 v119, v118
	s_nop 1
	v_permlane32_swap_b32_e32 v115, v114
	v_permlane32_swap_b32_e32 v119, v118
	v_add_f32_e32 v114, v114, v115
	v_add_f32_e32 v118, v118, v119
	s_nop 0
	v_readlane_b32 s0, v114, 0
	v_readlane_b32 s1, v114, 1
	s_nop 1
	v_fmac_f32_e32 v66, s0, v237
	v_fmac_f32_e32 v67, s1, v237
	v_mul_f32_e32 v74, v66, v66
	v_mul_f32_e32 v75, v67, v67
	v_readlane_b32 s0, v114, 2
	v_readlane_b32 s1, v114, 3
	s_nop 1
	v_fmac_f32_e32 v68, s0, v237
	v_fmac_f32_e32 v69, s1, v237
	v_mul_f32_e32 v76, v68, v68
	v_mul_f32_e32 v77, v69, v69
	v_readlane_b32 s0, v118, 0
	v_readlane_b32 s1, v118, 1
	s_nop 1
	v_fmac_f32_e32 v70, s0, v237
	v_fmac_f32_e32 v71, s1, v237
	v_mul_f32_e32 v78, v70, v70
	v_mul_f32_e32 v79, v71, v71
	v_readlane_b32 s0, v118, 2
	v_readlane_b32 s1, v118, 3
	s_nop 1
	v_fmac_f32_e32 v72, s0, v237
	v_fmac_f32_e32 v73, s1, v237
	v_mul_f32_e32 v80, v72, v72
	v_mul_f32_e32 v81, v73, v73
	v_cndmask_b32_e64 v115, v75, v74, s[98:99]
	v_cndmask_b32_e64 v117, v77, v76, s[98:99]
	v_cndmask_b32_e64 v119, v79, v78, s[98:99]
	v_cndmask_b32_e64 v121, v81, v80, s[98:99]
	v_cndmask_b32_e64 v114, v74, v75, s[98:99]
	v_cndmask_b32_e64 v116, v76, v77, s[98:99]
	v_cndmask_b32_e64 v118, v78, v79, s[98:99]
	v_cndmask_b32_e64 v120, v80, v81, s[98:99]
	v_add_f32_dpp v114, v115, v114 quad_perm:[1,0,3,2] row_mask:0xf bank_mask:0xf bound_ctrl:1
	v_add_f32_dpp v116, v117, v116 quad_perm:[1,0,3,2] row_mask:0xf bank_mask:0xf bound_ctrl:1
	v_add_f32_dpp v118, v119, v118 quad_perm:[1,0,3,2] row_mask:0xf bank_mask:0xf bound_ctrl:1
	v_add_f32_dpp v120, v121, v120 quad_perm:[1,0,3,2] row_mask:0xf bank_mask:0xf bound_ctrl:1
	v_cndmask_b32_e64 v115, v116, v114, s[100:101]
	v_cndmask_b32_e64 v119, v120, v118, s[100:101]
	v_cndmask_b32_e64 v114, v114, v116, s[100:101]
	v_cndmask_b32_e64 v118, v118, v120, s[100:101]
	v_add_f32_dpp v114, v115, v114 quad_perm:[2,3,0,1] row_mask:0xf bank_mask:0xf bound_ctrl:1
	v_add_f32_dpp v118, v119, v118 quad_perm:[2,3,0,1] row_mask:0xf bank_mask:0xf bound_ctrl:1
	s_nop 0
	v_add_f32_dpp v114, v114, v114 row_ror:4 row_mask:0xf bank_mask:0xf
	v_add_f32_dpp v118, v118, v118 row_ror:4 row_mask:0xf bank_mask:0xf
	s_nop 0
	v_add_f32_dpp v114, v114, v114 row_ror:8 row_mask:0xf bank_mask:0xf
	v_add_f32_dpp v118, v118, v118 row_ror:8 row_mask:0xf bank_mask:0xf
	v_mov_b32_e32 v115, v114
	v_mov_b32_e32 v119, v118
	s_nop 1
	v_permlane16_swap_b32_e32 v115, v114
	v_permlane16_swap_b32_e32 v119, v118
	v_add_f32_e32 v114, v114, v115
	v_add_f32_e32 v118, v118, v119
	v_mov_b32_e32 v115, v114
	v_mov_b32_e32 v119, v118
	s_nop 1
	v_permlane32_swap_b32_e32 v115, v114
	v_permlane32_swap_b32_e32 v119, v118
	v_add_f32_e32 v114, v114, v115
	v_add_f32_e32 v118, v118, v119
	s_nop 0
	v_readlane_b32 s0, v114, 0
	v_readlane_b32 s1, v114, 1
	s_nop 1
	v_fma_f32 v74, s0, v238, v234
	v_fma_f32 v75, s1, v238, v234
	v_rsq_f32_e32 v74, v74
	v_rsq_f32_e32 v75, v75
	v_readlane_b32 s0, v114, 2
	v_readlane_b32 s1, v114, 3
	s_nop 1
	v_fma_f32 v76, s0, v238, v234
	v_fma_f32 v77, s1, v238, v234
	v_rsq_f32_e32 v76, v76
	v_rsq_f32_e32 v77, v77
	v_readlane_b32 s0, v118, 0
	v_readlane_b32 s1, v118, 1
	s_nop 1
	v_fma_f32 v78, s0, v238, v234
	v_fma_f32 v79, s1, v238, v234
	v_rsq_f32_e32 v78, v78
	v_rsq_f32_e32 v79, v79
	v_readlane_b32 s0, v118, 2
	v_readlane_b32 s1, v118, 3
	s_nop 1
	v_fma_f32 v80, s0, v238, v234
	v_fma_f32 v81, s1, v238, v234
	v_rsq_f32_e32 v80, v80
	v_rsq_f32_e32 v81, v81
	s_waitcnt lgkmcnt(0)
	v_mul_f32_e32 v66, v66, v74
	v_fma_f32 v66, v220, v66, v213
	v_fmac_f32_e32 v66, v106, v90
	v_mul_f32_e32 v66, v98, v66
	s_or_b64 s[50:51], vcc, s[38:39]
	s_lshl_b64 s[50:51], s[50:51], 10
	v_cvt_pk_bf16_f32 v66, v66, v5
	v_lshl_add_u64 v[2:3], v[84:85], 0, s[50:51]
	global_store_short v[2:3], v66, off
	v_mul_f32_e32 v67, v67, v75
	v_fma_f32 v67, v220, v67, v213
	v_fmac_f32_e32 v67, v107, v91
	v_mul_f32_e32 v67, v99, v67
	s_or_b64 s[50:51], vcc, s[96:97]
	s_lshl_b64 s[50:51], s[50:51], 10
	v_cvt_pk_bf16_f32 v67, v67, v5
	v_lshl_add_u64 v[2:3], v[84:85], 0, s[50:51]
	global_store_short v[2:3], v67, off
	v_mul_f32_e32 v68, v68, v76
	v_fma_f32 v68, v220, v68, v213
	v_fmac_f32_e32 v68, v108, v92
	v_mul_f32_e32 v68, v100, v68
	s_or_b64 s[50:51], vcc, s[48:49]
	s_lshl_b64 s[50:51], s[50:51], 10
	v_cvt_pk_bf16_f32 v68, v68, v5
	v_lshl_add_u64 v[2:3], v[84:85], 0, s[50:51]
	global_store_short v[2:3], v68, off
	v_mul_f32_e32 v69, v69, v77
	v_fma_f32 v69, v220, v69, v213
	v_fmac_f32_e32 v69, v109, v93
	v_mul_f32_e32 v69, v101, v69
	s_or_b64 s[50:51], vcc, s[60:61]
	s_lshl_b64 s[50:51], s[50:51], 10
	v_cvt_pk_bf16_f32 v69, v69, v5
	v_lshl_add_u64 v[2:3], v[84:85], 0, s[50:51]
	global_store_short v[2:3], v69, off
	v_mul_f32_e32 v70, v70, v78
	v_fma_f32 v70, v220, v70, v213
	v_fmac_f32_e32 v70, v110, v94
	v_mul_f32_e32 v70, v102, v70
	s_or_b64 s[50:51], vcc, s[54:55]
	s_lshl_b64 s[50:51], s[50:51], 10
	v_cvt_pk_bf16_f32 v70, v70, v5
	v_lshl_add_u64 v[2:3], v[84:85], 0, s[50:51]
	global_store_short v[2:3], v70, off
	v_mul_f32_e32 v71, v71, v79
	v_fma_f32 v71, v220, v71, v213
	v_fmac_f32_e32 v71, v111, v95
	v_mul_f32_e32 v71, v103, v71
	s_or_b64 s[50:51], vcc, s[74:75]
	s_lshl_b64 s[50:51], s[50:51], 10
	v_cvt_pk_bf16_f32 v71, v71, v5
	v_lshl_add_u64 v[2:3], v[84:85], 0, s[50:51]
	global_store_short v[2:3], v71, off
	v_mul_f32_e32 v72, v72, v80
	v_fma_f32 v72, v220, v72, v213
	v_fmac_f32_e32 v72, v112, v96
	v_mul_f32_e32 v72, v104, v72
	s_or_b64 s[50:51], vcc, s[76:77]
	s_lshl_b64 s[50:51], s[50:51], 10
	v_cvt_pk_bf16_f32 v72, v72, v5
	v_lshl_add_u64 v[2:3], v[84:85], 0, s[50:51]
	global_store_short v[2:3], v72, off
	v_mul_f32_e32 v73, v73, v81
	v_fma_f32 v73, v220, v73, v213
	v_fmac_f32_e32 v73, v113, v97
	v_mul_f32_e32 v73, v105, v73
	s_or_b64 s[50:51], vcc, s[80:81]
	s_lshl_b64 s[50:51], s[50:51], 10
	v_cvt_pk_bf16_f32 v73, v73, v5
	v_lshl_add_u64 v[2:3], v[84:85], 0, s[50:51]
	global_store_short v[2:3], v73, off
	s_cmp_lg_u32 s42, 63
	s_cselect_b64 s[72:73], -1, 0
	s_branch .LBB0_2494
